# in-proj epilogue V heads: transposed V-cache store staged through the wave's own idle LDS-DMA slices (16 ds_write_b32 + 2 ds_read_b128) and written with 2 full-wave dwordx4 stores per row group instea
# speedup vs baseline: 1.0075x; 1.0075x over previous
; DI size_t vf_off(int h, int nblk, int krow, int d) { const int kk = krow & 31; return (((((size_t)h * nblk + (krow >> 5)) * 2 + (d >> 5)) * 2 + (kk >> 4)) * 64 + ((kk >> 2) & 1) * 32 + (d & 31)) * 8 + 4 * ((kk >> 3) & 1) + (kk & 3); }
;     DI void operator()(const AccT& acc, const Unit& u, int wr, int wc, int fr, int fq, LAS unsigned char*) const {
;     ...
;                     } else {
;                         bf16_t* vp = (bf16_t*)(ws + (isA ? WS_VTA : WS_VTB));
; #pragma unroll
;                         for (int bj = 0; bj < 2; ++bj)
; #pragma unroll
;                             for (int n = 0; n < 2; ++n)
; #pragma unroll
;                                 for (int j = 0; j < 4; ++j) {
;                                     const float mine = v[bj][n][j], oth = __shfl_xor(mine, 1);
;                                     if (!(fr & 1)) *(unsigned*)(vp + vf_off(h, krows >> 5, krow, 32 * bj + 16 * n + 4 * fq + j)) = pk2(mine, oth);
;                                 }
.LBB0_142:
	s_or_b64 exec, exec, s[10:11]
	v_lshrrev_b32_e32 v183, 6, v183
	v_or_b32_e32 v150, s90, v167
	v_mad_u64_u32 v[184:185], s[10:11], s31, v183, v[150:151]
	v_cmp_gt_i32_e32 vcc, s68, v182
	s_mov_b64 s[10:11], -1
	s_nop 0
	v_cndmask_b32_e32 v183, v184, v182, vcc
	v_ashrrev_i32_e32 v184, 5, v183
	s_and_b64 vcc, exec, s[50:51]
	v_ashrrev_i32_e32 v185, 31, v184
	s_cbranch_vccz .LBB0_176
	v_readfirstlane_b32 s58, v183
	v_and_b32_e32 v150, 15, v198
	v_lshrrev_b32_e32 v186, 4, v198
	v_bfe_u32 v187, v150, 2, 1
	v_lshrrev_b32_e32 v188, 3, v150
	v_and_b32_e32 v150, 3, v150
	v_lshl_add_u32 v150, v188, 2, v150
	v_lshl_add_u32 v186, v187, 3, v186
	v_lshlrev_b32_e32 v186, 6, v186
	v_lshl_add_u32 v186, v150, 1, v186
	s_add_i32 s59, s64, 0xc000
	v_add_u32_e32 v186, s59, v186
	v_lshlrev_b32_e32 v188, 4, v198
	v_add_u32_e32 v187, s59, v188
	s_lshr_b32 s56, s58, 5
	s_add_u32 s56, s56, s46
	s_lshl_b32 s56, s56, 12
	s_and_b32 s57, s58, 16
	s_lshl_b32 s57, s57, 6
	s_add_u32 s56, s56, s57
	s_add_u32 s56, s56, s91
	s_add_u32 s56, s36, s56
	s_addc_u32 s57, s37, 0
	v_mov_b32_dpp v189, v140 quad_perm:[1,0,3,2] row_mask:0xf bank_mask:0xf
	v_mov_b32_dpp v199, v141 quad_perm:[1,0,3,2] row_mask:0xf bank_mask:0xf
	v_cvt_pk_bf16_f32 v140, v140, v189
	v_mov_b32_dpp v189, v142 quad_perm:[1,0,3,2] row_mask:0xf bank_mask:0xf
	v_cvt_pk_bf16_f32 v141, v141, v199
	v_mov_b32_dpp v199, v143 quad_perm:[1,0,3,2] row_mask:0xf bank_mask:0xf
	v_cvt_pk_bf16_f32 v142, v142, v189
	v_mov_b32_dpp v189, v136 quad_perm:[1,0,3,2] row_mask:0xf bank_mask:0xf
	v_cvt_pk_bf16_f32 v143, v143, v199
	v_mov_b32_dpp v199, v137 quad_perm:[1,0,3,2] row_mask:0xf bank_mask:0xf
	v_cvt_pk_bf16_f32 v136, v136, v189
	v_mov_b32_dpp v189, v138 quad_perm:[1,0,3,2] row_mask:0xf bank_mask:0xf
	v_cvt_pk_bf16_f32 v137, v137, v199
	v_mov_b32_dpp v199, v139 quad_perm:[1,0,3,2] row_mask:0xf bank_mask:0xf
	v_cvt_pk_bf16_f32 v138, v138, v189
	v_mov_b32_dpp v189, v132 quad_perm:[1,0,3,2] row_mask:0xf bank_mask:0xf
	v_cvt_pk_bf16_f32 v139, v139, v199
	v_mov_b32_dpp v199, v133 quad_perm:[1,0,3,2] row_mask:0xf bank_mask:0xf
	v_cvt_pk_bf16_f32 v132, v132, v189
	v_mov_b32_dpp v189, v134 quad_perm:[1,0,3,2] row_mask:0xf bank_mask:0xf
	v_cvt_pk_bf16_f32 v133, v133, v199
	v_mov_b32_dpp v199, v135 quad_perm:[1,0,3,2] row_mask:0xf bank_mask:0xf
	v_cvt_pk_bf16_f32 v134, v134, v189
	v_mov_b32_dpp v189, v128 quad_perm:[1,0,3,2] row_mask:0xf bank_mask:0xf
	v_cvt_pk_bf16_f32 v135, v135, v199
	v_mov_b32_dpp v199, v129 quad_perm:[1,0,3,2] row_mask:0xf bank_mask:0xf
	v_cvt_pk_bf16_f32 v128, v128, v189
	v_mov_b32_dpp v189, v130 quad_perm:[1,0,3,2] row_mask:0xf bank_mask:0xf
	v_cvt_pk_bf16_f32 v129, v129, v199
	v_mov_b32_dpp v199, v131 quad_perm:[1,0,3,2] row_mask:0xf bank_mask:0xf
	v_cvt_pk_bf16_f32 v130, v130, v189
	v_cvt_pk_bf16_f32 v131, v131, v199
	s_and_saveexec_b64 s[10:11], s[12:13]
	ds_write_b32 v186, v140
	ds_write_b32 v186, v141 offset:16
	ds_write_b32 v186, v142 offset:32
	ds_write_b32 v186, v143 offset:48
	ds_write_b32 v186, v136 offset:256
	ds_write_b32 v186, v137 offset:272
	ds_write_b32 v186, v138 offset:288
	ds_write_b32 v186, v139 offset:304
	ds_write_b32 v186, v132 offset:8192
	ds_write_b32 v186, v133 offset:8208
	ds_write_b32 v186, v134 offset:8224
	ds_write_b32 v186, v135 offset:8240
	ds_write_b32 v186, v128 offset:8448
	ds_write_b32 v186, v129 offset:8464
	ds_write_b32 v186, v130 offset:8480
	ds_write_b32 v186, v131 offset:8496
	s_mov_b64 exec, s[10:11]
	ds_read_b128 v[140:143], v187
	ds_read_b128 v[136:139], v187 offset:8192
	s_waitcnt lgkmcnt(0)
	global_store_dwordx4 v188, v[140:143], s[56:57]
	global_store_dwordx4 v188, v[136:139], s[56:57] offset:2048

; DI size_t vf_off(int h, int nblk, int krow, int d) { const int kk = krow & 31; return (((((size_t)h * nblk + (krow >> 5)) * 2 + (d >> 5)) * 2 + (kk >> 4)) * 64 + ((kk >> 2) & 1) * 32 + (d & 31)) * 8 + 4 * ((kk >> 3) & 1) + (kk & 3); }
;     DI void operator()(const AccT& acc, const Unit& u, int wr, int wc, int fr, int fq, LAS unsigned char*) const {
;     ...
;                     } else {
;                         bf16_t* vp = (bf16_t*)(ws + (isA ? WS_VTA : WS_VTB));
; #pragma unroll
;                         for (int bj = 0; bj < 2; ++bj)
; #pragma unroll
;                             for (int n = 0; n < 2; ++n)
; #pragma unroll
;                                 for (int j = 0; j < 4; ++j) {
;                                     const float mine = v[bj][n][j], oth = __shfl_xor(mine, 1);
;                                     if (!(fr & 1)) *(unsigned*)(vp + vf_off(h, krows >> 5, krow, 32 * bj + 16 * n + 4 * fq + j)) = pk2(mine, oth);
;                                 }
.LBB0_192:
	s_or_b64 exec, exec, s[0:1]
	v_lshrrev_b32_e32 v129, 6, v129
	v_or_b32_e32 v130, s90, v191
	v_mad_u64_u32 v[130:131], s[0:1], s31, v129, v[130:131]
	v_cmp_gt_i32_e32 vcc, s68, v128
	s_mov_b64 s[0:1], -1
	s_nop 0
	v_cndmask_b32_e32 v129, v130, v128, vcc
	v_ashrrev_i32_e32 v130, 5, v129
	s_andn2_b64 vcc, exec, s[50:51]
	v_ashrrev_i32_e32 v131, 31, v130
	s_cbranch_vccnz .LBB0_226
	v_readfirstlane_b32 s58, v129
	v_and_b32_e32 v132, 15, v198
	v_lshrrev_b32_e32 v133, 4, v198
	v_bfe_u32 v134, v132, 2, 1
	v_lshrrev_b32_e32 v135, 3, v132
	v_and_b32_e32 v132, 3, v132
	v_lshl_add_u32 v132, v135, 2, v132
	v_lshl_add_u32 v133, v134, 3, v133
	v_lshlrev_b32_e32 v133, 6, v133
	v_lshl_add_u32 v133, v132, 1, v133
	s_add_i32 s59, s64, 0xc000
	v_add_u32_e32 v133, s59, v133
	v_lshlrev_b32_e32 v135, 4, v198
	v_add_u32_e32 v134, s59, v135
	s_lshr_b32 s56, s58, 5
	s_add_u32 s56, s56, s46
	s_lshl_b32 s56, s56, 12
	s_and_b32 s57, s58, 16
	s_lshl_b32 s57, s57, 6
	s_add_u32 s56, s56, s57
	s_add_u32 s56, s56, s91
	s_add_u32 s56, s36, s56
	s_addc_u32 s57, s37, 0
	v_mov_b32_dpp v136, v124 quad_perm:[1,0,3,2] row_mask:0xf bank_mask:0xf
	v_mov_b32_dpp v137, v125 quad_perm:[1,0,3,2] row_mask:0xf bank_mask:0xf
	v_cvt_pk_bf16_f32 v124, v124, v136
	v_mov_b32_dpp v136, v126 quad_perm:[1,0,3,2] row_mask:0xf bank_mask:0xf
	v_cvt_pk_bf16_f32 v125, v125, v137
	v_mov_b32_dpp v137, v127 quad_perm:[1,0,3,2] row_mask:0xf bank_mask:0xf
	v_cvt_pk_bf16_f32 v126, v126, v136
	v_mov_b32_dpp v136, v120 quad_perm:[1,0,3,2] row_mask:0xf bank_mask:0xf
	v_cvt_pk_bf16_f32 v127, v127, v137
	v_mov_b32_dpp v137, v121 quad_perm:[1,0,3,2] row_mask:0xf bank_mask:0xf
	v_cvt_pk_bf16_f32 v120, v120, v136
	v_mov_b32_dpp v136, v122 quad_perm:[1,0,3,2] row_mask:0xf bank_mask:0xf
	v_cvt_pk_bf16_f32 v121, v121, v137
	v_mov_b32_dpp v137, v123 quad_perm:[1,0,3,2] row_mask:0xf bank_mask:0xf
	v_cvt_pk_bf16_f32 v122, v122, v136
	v_mov_b32_dpp v136, v116 quad_perm:[1,0,3,2] row_mask:0xf bank_mask:0xf
	v_cvt_pk_bf16_f32 v123, v123, v137
	v_mov_b32_dpp v137, v117 quad_perm:[1,0,3,2] row_mask:0xf bank_mask:0xf
	v_cvt_pk_bf16_f32 v116, v116, v136
	v_mov_b32_dpp v136, v118 quad_perm:[1,0,3,2] row_mask:0xf bank_mask:0xf
	v_cvt_pk_bf16_f32 v117, v117, v137
	v_mov_b32_dpp v137, v119 quad_perm:[1,0,3,2] row_mask:0xf bank_mask:0xf
	v_cvt_pk_bf16_f32 v118, v118, v136
	v_mov_b32_dpp v136, v112 quad_perm:[1,0,3,2] row_mask:0xf bank_mask:0xf
	v_cvt_pk_bf16_f32 v119, v119, v137
	v_mov_b32_dpp v137, v113 quad_perm:[1,0,3,2] row_mask:0xf bank_mask:0xf
	v_cvt_pk_bf16_f32 v112, v112, v136
	v_mov_b32_dpp v136, v114 quad_perm:[1,0,3,2] row_mask:0xf bank_mask:0xf
	v_cvt_pk_bf16_f32 v113, v113, v137
	v_mov_b32_dpp v137, v115 quad_perm:[1,0,3,2] row_mask:0xf bank_mask:0xf
	v_cvt_pk_bf16_f32 v114, v114, v136
	v_cvt_pk_bf16_f32 v115, v115, v137
	s_and_saveexec_b64 s[0:1], s[12:13]
	ds_write_b32 v133, v124
	ds_write_b32 v133, v125 offset:16
	ds_write_b32 v133, v126 offset:32
	ds_write_b32 v133, v127 offset:48
	ds_write_b32 v133, v120 offset:256
	ds_write_b32 v133, v121 offset:272
	ds_write_b32 v133, v122 offset:288
	ds_write_b32 v133, v123 offset:304
	ds_write_b32 v133, v116 offset:8192
	ds_write_b32 v133, v117 offset:8208
	ds_write_b32 v133, v118 offset:8224
	ds_write_b32 v133, v119 offset:8240
	ds_write_b32 v133, v112 offset:8448
	ds_write_b32 v133, v113 offset:8464
	ds_write_b32 v133, v114 offset:8480
	ds_write_b32 v133, v115 offset:8496
	s_mov_b64 exec, s[0:1]
	ds_read_b128 v[124:127], v134
	ds_read_b128 v[120:123], v134 offset:8192
	s_waitcnt lgkmcnt(0)
	global_store_dwordx4 v135, v[124:127], s[56:57]
	global_store_dwordx4 v135, v[120:123], s[56:57] offset:2048

; DI size_t vf_off(int h, int nblk, int krow, int d) { const int kk = krow & 31; return (((((size_t)h * nblk + (krow >> 5)) * 2 + (d >> 5)) * 2 + (kk >> 4)) * 64 + ((kk >> 2) & 1) * 32 + (d & 31)) * 8 + 4 * ((kk >> 3) & 1) + (kk & 3); }
;     DI void operator()(const AccT& acc, const Unit& u, int wr, int wc, int fr, int fq, LAS unsigned char*) const {
;     ...
;                     } else {
;                         bf16_t* vp = (bf16_t*)(ws + (isA ? WS_VTA : WS_VTB));
; #pragma unroll
;                         for (int bj = 0; bj < 2; ++bj)
; #pragma unroll
;                             for (int n = 0; n < 2; ++n)
; #pragma unroll
;                                 for (int j = 0; j < 4; ++j) {
;                                     const float mine = v[bj][n][j], oth = __shfl_xor(mine, 1);
;                                     if (!(fr & 1)) *(unsigned*)(vp + vf_off(h, krows >> 5, krow, 32 * bj + 16 * n + 4 * fq + j)) = pk2(mine, oth);
;                                 }
.LBB0_238:
	s_or_b64 exec, exec, s[0:1]
	v_lshrrev_b32_e32 v113, 6, v113
	v_or_b32_e32 v114, s90, v192
	v_mad_u64_u32 v[114:115], s[0:1], s31, v113, v[114:115]
	v_cmp_gt_i32_e32 vcc, s68, v112
	s_mov_b64 s[0:1], -1
	s_nop 0
	v_cndmask_b32_e32 v113, v114, v112, vcc
	v_ashrrev_i32_e32 v114, 5, v113
	s_andn2_b64 vcc, exec, s[50:51]
	v_ashrrev_i32_e32 v115, 31, v114
	s_cbranch_vccnz .LBB0_272
	v_readfirstlane_b32 s58, v113
	v_and_b32_e32 v116, 15, v198
	v_lshrrev_b32_e32 v117, 4, v198
	v_bfe_u32 v118, v116, 2, 1
	v_lshrrev_b32_e32 v119, 3, v116
	v_and_b32_e32 v116, 3, v116
	v_lshl_add_u32 v116, v119, 2, v116
	v_lshl_add_u32 v117, v118, 3, v117
	v_lshlrev_b32_e32 v117, 6, v117
	v_lshl_add_u32 v117, v116, 1, v117
	s_add_i32 s59, s64, 0xc000
	v_add_u32_e32 v117, s59, v117
	v_lshlrev_b32_e32 v119, 4, v198
	v_add_u32_e32 v118, s59, v119
	s_lshr_b32 s56, s58, 5
	s_add_u32 s56, s56, s46
	s_lshl_b32 s56, s56, 12
	s_and_b32 s57, s58, 16
	s_lshl_b32 s57, s57, 6
	s_add_u32 s56, s56, s57
	s_add_u32 s56, s56, s91
	s_add_u32 s56, s36, s56
	s_addc_u32 s57, s37, 0
	v_mov_b32_dpp v120, v108 quad_perm:[1,0,3,2] row_mask:0xf bank_mask:0xf
	v_mov_b32_dpp v121, v109 quad_perm:[1,0,3,2] row_mask:0xf bank_mask:0xf
	v_cvt_pk_bf16_f32 v108, v108, v120
	v_mov_b32_dpp v120, v110 quad_perm:[1,0,3,2] row_mask:0xf bank_mask:0xf
	v_cvt_pk_bf16_f32 v109, v109, v121
	v_mov_b32_dpp v121, v111 quad_perm:[1,0,3,2] row_mask:0xf bank_mask:0xf
	v_cvt_pk_bf16_f32 v110, v110, v120
	v_mov_b32_dpp v120, v104 quad_perm:[1,0,3,2] row_mask:0xf bank_mask:0xf
	v_cvt_pk_bf16_f32 v111, v111, v121
	v_mov_b32_dpp v121, v105 quad_perm:[1,0,3,2] row_mask:0xf bank_mask:0xf
	v_cvt_pk_bf16_f32 v104, v104, v120
	v_mov_b32_dpp v120, v106 quad_perm:[1,0,3,2] row_mask:0xf bank_mask:0xf
	v_cvt_pk_bf16_f32 v105, v105, v121
	v_mov_b32_dpp v121, v107 quad_perm:[1,0,3,2] row_mask:0xf bank_mask:0xf
	v_cvt_pk_bf16_f32 v106, v106, v120
	v_mov_b32_dpp v120, v100 quad_perm:[1,0,3,2] row_mask:0xf bank_mask:0xf
	v_cvt_pk_bf16_f32 v107, v107, v121
	v_mov_b32_dpp v121, v101 quad_perm:[1,0,3,2] row_mask:0xf bank_mask:0xf
	v_cvt_pk_bf16_f32 v100, v100, v120
	v_mov_b32_dpp v120, v102 quad_perm:[1,0,3,2] row_mask:0xf bank_mask:0xf
	v_cvt_pk_bf16_f32 v101, v101, v121
	v_mov_b32_dpp v121, v103 quad_perm:[1,0,3,2] row_mask:0xf bank_mask:0xf
	v_cvt_pk_bf16_f32 v102, v102, v120
	v_mov_b32_dpp v120, v96 quad_perm:[1,0,3,2] row_mask:0xf bank_mask:0xf
	v_cvt_pk_bf16_f32 v103, v103, v121
	v_mov_b32_dpp v121, v97 quad_perm:[1,0,3,2] row_mask:0xf bank_mask:0xf
	v_cvt_pk_bf16_f32 v96, v96, v120
	v_mov_b32_dpp v120, v98 quad_perm:[1,0,3,2] row_mask:0xf bank_mask:0xf
	v_cvt_pk_bf16_f32 v97, v97, v121
	v_mov_b32_dpp v121, v99 quad_perm:[1,0,3,2] row_mask:0xf bank_mask:0xf
	v_cvt_pk_bf16_f32 v98, v98, v120
	v_cvt_pk_bf16_f32 v99, v99, v121
	s_and_saveexec_b64 s[0:1], s[12:13]
	ds_write_b32 v117, v108
	ds_write_b32 v117, v109 offset:16
	ds_write_b32 v117, v110 offset:32
	ds_write_b32 v117, v111 offset:48
	ds_write_b32 v117, v104 offset:256
	ds_write_b32 v117, v105 offset:272
	ds_write_b32 v117, v106 offset:288
	ds_write_b32 v117, v107 offset:304
	ds_write_b32 v117, v100 offset:8192
	ds_write_b32 v117, v101 offset:8208
	ds_write_b32 v117, v102 offset:8224
	ds_write_b32 v117, v103 offset:8240
	ds_write_b32 v117, v96 offset:8448
	ds_write_b32 v117, v97 offset:8464
	ds_write_b32 v117, v98 offset:8480
	ds_write_b32 v117, v99 offset:8496
	s_mov_b64 exec, s[0:1]
	ds_read_b128 v[108:111], v118
	ds_read_b128 v[104:107], v118 offset:8192
	s_waitcnt lgkmcnt(0)
	global_store_dwordx4 v119, v[108:111], s[56:57]
	global_store_dwordx4 v119, v[104:107], s[56:57] offset:2048

; DI size_t vf_off(int h, int nblk, int krow, int d) { const int kk = krow & 31; return (((((size_t)h * nblk + (krow >> 5)) * 2 + (d >> 5)) * 2 + (kk >> 4)) * 64 + ((kk >> 2) & 1) * 32 + (d & 31)) * 8 + 4 * ((kk >> 3) & 1) + (kk & 3); }
;     DI void operator()(const AccT& acc, const Unit& u, int wr, int wc, int fr, int fq, LAS unsigned char*) const {
;     ...
;                     } else {
;                         bf16_t* vp = (bf16_t*)(ws + (isA ? WS_VTA : WS_VTB));
; #pragma unroll
;                         for (int bj = 0; bj < 2; ++bj)
; #pragma unroll
;                             for (int n = 0; n < 2; ++n)
; #pragma unroll
;                                 for (int j = 0; j < 4; ++j) {
;                                     const float mine = v[bj][n][j], oth = __shfl_xor(mine, 1);
;                                     if (!(fr & 1)) *(unsigned*)(vp + vf_off(h, krows >> 5, krow, 32 * bj + 16 * n + 4 * fq + j)) = pk2(mine, oth);
;                                 }
.LBB0_284:
	s_or_b64 exec, exec, s[0:1]
	v_lshrrev_b32_e32 v97, 6, v97
	v_or_b32_e32 v98, s90, v193
	v_mad_u64_u32 v[98:99], s[0:1], s31, v97, v[98:99]
	v_cmp_gt_i32_e32 vcc, s68, v96
	s_mov_b64 s[0:1], -1
	s_nop 0
	v_cndmask_b32_e32 v97, v98, v96, vcc
	v_ashrrev_i32_e32 v98, 5, v97
	s_andn2_b64 vcc, exec, s[50:51]
	v_ashrrev_i32_e32 v99, 31, v98
	s_cbranch_vccnz .LBB0_318
	v_readfirstlane_b32 s58, v97
	v_and_b32_e32 v100, 15, v198
	v_lshrrev_b32_e32 v101, 4, v198
	v_bfe_u32 v102, v100, 2, 1
	v_lshrrev_b32_e32 v103, 3, v100
	v_and_b32_e32 v100, 3, v100
	v_lshl_add_u32 v100, v103, 2, v100
	v_lshl_add_u32 v101, v102, 3, v101
	v_lshlrev_b32_e32 v101, 6, v101
	v_lshl_add_u32 v101, v100, 1, v101
	s_add_i32 s59, s64, 0xc000
	v_add_u32_e32 v101, s59, v101
	v_lshlrev_b32_e32 v103, 4, v198
	v_add_u32_e32 v102, s59, v103
	s_lshr_b32 s56, s58, 5
	s_add_u32 s56, s56, s46
	s_lshl_b32 s56, s56, 12
	s_and_b32 s57, s58, 16
	s_lshl_b32 s57, s57, 6
	s_add_u32 s56, s56, s57
	s_add_u32 s56, s56, s91
	s_add_u32 s56, s36, s56
	s_addc_u32 s57, s37, 0
	v_mov_b32_dpp v104, v92 quad_perm:[1,0,3,2] row_mask:0xf bank_mask:0xf
	v_mov_b32_dpp v105, v93 quad_perm:[1,0,3,2] row_mask:0xf bank_mask:0xf
	v_cvt_pk_bf16_f32 v92, v92, v104
	v_mov_b32_dpp v104, v94 quad_perm:[1,0,3,2] row_mask:0xf bank_mask:0xf
	v_cvt_pk_bf16_f32 v93, v93, v105
	v_mov_b32_dpp v105, v95 quad_perm:[1,0,3,2] row_mask:0xf bank_mask:0xf
	v_cvt_pk_bf16_f32 v94, v94, v104
	v_mov_b32_dpp v104, v88 quad_perm:[1,0,3,2] row_mask:0xf bank_mask:0xf
	v_cvt_pk_bf16_f32 v95, v95, v105
	v_mov_b32_dpp v105, v89 quad_perm:[1,0,3,2] row_mask:0xf bank_mask:0xf
	v_cvt_pk_bf16_f32 v88, v88, v104
	v_mov_b32_dpp v104, v90 quad_perm:[1,0,3,2] row_mask:0xf bank_mask:0xf
	v_cvt_pk_bf16_f32 v89, v89, v105
	v_mov_b32_dpp v105, v91 quad_perm:[1,0,3,2] row_mask:0xf bank_mask:0xf
	v_cvt_pk_bf16_f32 v90, v90, v104
	v_mov_b32_dpp v104, v84 quad_perm:[1,0,3,2] row_mask:0xf bank_mask:0xf
	v_cvt_pk_bf16_f32 v91, v91, v105
	v_mov_b32_dpp v105, v85 quad_perm:[1,0,3,2] row_mask:0xf bank_mask:0xf
	v_cvt_pk_bf16_f32 v84, v84, v104
	v_mov_b32_dpp v104, v86 quad_perm:[1,0,3,2] row_mask:0xf bank_mask:0xf
	v_cvt_pk_bf16_f32 v85, v85, v105
	v_mov_b32_dpp v105, v87 quad_perm:[1,0,3,2] row_mask:0xf bank_mask:0xf
	v_cvt_pk_bf16_f32 v86, v86, v104
	v_mov_b32_dpp v104, v80 quad_perm:[1,0,3,2] row_mask:0xf bank_mask:0xf
	v_cvt_pk_bf16_f32 v87, v87, v105
	v_mov_b32_dpp v105, v81 quad_perm:[1,0,3,2] row_mask:0xf bank_mask:0xf
	v_cvt_pk_bf16_f32 v80, v80, v104
	v_mov_b32_dpp v104, v82 quad_perm:[1,0,3,2] row_mask:0xf bank_mask:0xf
	v_cvt_pk_bf16_f32 v81, v81, v105
	v_mov_b32_dpp v105, v83 quad_perm:[1,0,3,2] row_mask:0xf bank_mask:0xf
	v_cvt_pk_bf16_f32 v82, v82, v104
	v_cvt_pk_bf16_f32 v83, v83, v105
	s_and_saveexec_b64 s[0:1], s[12:13]
	ds_write_b32 v101, v92
	ds_write_b32 v101, v93 offset:16
	ds_write_b32 v101, v94 offset:32
	ds_write_b32 v101, v95 offset:48
	ds_write_b32 v101, v88 offset:256
	ds_write_b32 v101, v89 offset:272
	ds_write_b32 v101, v90 offset:288
	ds_write_b32 v101, v91 offset:304
	ds_write_b32 v101, v84 offset:8192
	ds_write_b32 v101, v85 offset:8208
	ds_write_b32 v101, v86 offset:8224
	ds_write_b32 v101, v87 offset:8240
	ds_write_b32 v101, v80 offset:8448
	ds_write_b32 v101, v81 offset:8464
	ds_write_b32 v101, v82 offset:8480
	ds_write_b32 v101, v83 offset:8496
	s_mov_b64 exec, s[0:1]
	ds_read_b128 v[92:95], v102
	ds_read_b128 v[88:91], v102 offset:8192
	s_waitcnt lgkmcnt(0)
	global_store_dwordx4 v103, v[92:95], s[56:57]
	global_store_dwordx4 v103, v[88:91], s[56:57] offset:2048

; DI size_t vf_off(int h, int nblk, int krow, int d) { const int kk = krow & 31; return (((((size_t)h * nblk + (krow >> 5)) * 2 + (d >> 5)) * 2 + (kk >> 4)) * 64 + ((kk >> 2) & 1) * 32 + (d & 31)) * 8 + 4 * ((kk >> 3) & 1) + (kk & 3); }
;     DI void operator()(const AccT& acc, const Unit& u, int wr, int wc, int fr, int fq, LAS unsigned char*) const {
;     ...
;                     } else {
;                         bf16_t* vp = (bf16_t*)(ws + (isA ? WS_VTA : WS_VTB));
; #pragma unroll
;                         for (int bj = 0; bj < 2; ++bj)
; #pragma unroll
;                             for (int n = 0; n < 2; ++n)
; #pragma unroll
;                                 for (int j = 0; j < 4; ++j) {
;                                     const float mine = v[bj][n][j], oth = __shfl_xor(mine, 1);
;                                     if (!(fr & 1)) *(unsigned*)(vp + vf_off(h, krows >> 5, krow, 32 * bj + 16 * n + 4 * fq + j)) = pk2(mine, oth);
;                                 }
.LBB0_330:
	s_or_b64 exec, exec, s[0:1]
	v_lshrrev_b32_e32 v81, 6, v81
	v_or_b32_e32 v82, s90, v167
	v_mad_u64_u32 v[82:83], s[0:1], s31, v81, v[82:83]
	v_cmp_gt_i32_e32 vcc, s68, v80
	s_mov_b64 s[0:1], -1
	s_nop 0
	v_cndmask_b32_e32 v81, v82, v80, vcc
	v_ashrrev_i32_e32 v82, 5, v81
	s_andn2_b64 vcc, exec, s[50:51]
	v_ashrrev_i32_e32 v83, 31, v82
	s_cbranch_vccnz .LBB0_364
	v_readfirstlane_b32 s58, v81
	v_and_b32_e32 v84, 15, v198
	v_lshrrev_b32_e32 v85, 4, v198
	v_bfe_u32 v86, v84, 2, 1
	v_lshrrev_b32_e32 v87, 3, v84
	v_and_b32_e32 v84, 3, v84
	v_lshl_add_u32 v84, v87, 2, v84
	v_lshl_add_u32 v85, v86, 3, v85
	v_lshlrev_b32_e32 v85, 6, v85
	v_lshl_add_u32 v85, v84, 1, v85
	s_add_i32 s59, s64, 0xc000
	v_add_u32_e32 v85, s59, v85
	v_lshlrev_b32_e32 v87, 4, v198
	v_add_u32_e32 v86, s59, v87
	s_lshr_b32 s56, s58, 5
	s_add_u32 s56, s56, s46
	s_lshl_b32 s56, s56, 12
	s_and_b32 s57, s58, 16
	s_lshl_b32 s57, s57, 6
	s_add_u32 s56, s56, s57
	s_add_u32 s56, s56, s91
	s_add_u32 s56, s36, s56
	s_addc_u32 s57, s37, 0
	v_mov_b32_dpp v88, v76 quad_perm:[1,0,3,2] row_mask:0xf bank_mask:0xf
	v_mov_b32_dpp v89, v77 quad_perm:[1,0,3,2] row_mask:0xf bank_mask:0xf
	v_cvt_pk_bf16_f32 v76, v76, v88
	v_mov_b32_dpp v88, v78 quad_perm:[1,0,3,2] row_mask:0xf bank_mask:0xf
	v_cvt_pk_bf16_f32 v77, v77, v89
	v_mov_b32_dpp v89, v79 quad_perm:[1,0,3,2] row_mask:0xf bank_mask:0xf
	v_cvt_pk_bf16_f32 v78, v78, v88
	v_mov_b32_dpp v88, v72 quad_perm:[1,0,3,2] row_mask:0xf bank_mask:0xf
	v_cvt_pk_bf16_f32 v79, v79, v89
	v_mov_b32_dpp v89, v73 quad_perm:[1,0,3,2] row_mask:0xf bank_mask:0xf
	v_cvt_pk_bf16_f32 v72, v72, v88
	v_mov_b32_dpp v88, v74 quad_perm:[1,0,3,2] row_mask:0xf bank_mask:0xf
	v_cvt_pk_bf16_f32 v73, v73, v89
	v_mov_b32_dpp v89, v75 quad_perm:[1,0,3,2] row_mask:0xf bank_mask:0xf
	v_cvt_pk_bf16_f32 v74, v74, v88
	v_mov_b32_dpp v88, v68 quad_perm:[1,0,3,2] row_mask:0xf bank_mask:0xf
	v_cvt_pk_bf16_f32 v75, v75, v89
	v_mov_b32_dpp v89, v69 quad_perm:[1,0,3,2] row_mask:0xf bank_mask:0xf
	v_cvt_pk_bf16_f32 v68, v68, v88
	v_mov_b32_dpp v88, v70 quad_perm:[1,0,3,2] row_mask:0xf bank_mask:0xf
	v_cvt_pk_bf16_f32 v69, v69, v89
	v_mov_b32_dpp v89, v71 quad_perm:[1,0,3,2] row_mask:0xf bank_mask:0xf
	v_cvt_pk_bf16_f32 v70, v70, v88
	v_mov_b32_dpp v88, v64 quad_perm:[1,0,3,2] row_mask:0xf bank_mask:0xf
	v_cvt_pk_bf16_f32 v71, v71, v89
	v_mov_b32_dpp v89, v65 quad_perm:[1,0,3,2] row_mask:0xf bank_mask:0xf
	v_cvt_pk_bf16_f32 v64, v64, v88
	v_mov_b32_dpp v88, v66 quad_perm:[1,0,3,2] row_mask:0xf bank_mask:0xf
	v_cvt_pk_bf16_f32 v65, v65, v89
	v_mov_b32_dpp v89, v67 quad_perm:[1,0,3,2] row_mask:0xf bank_mask:0xf
	v_cvt_pk_bf16_f32 v66, v66, v88
	v_cvt_pk_bf16_f32 v67, v67, v89
	s_and_saveexec_b64 s[0:1], s[12:13]
	ds_write_b32 v85, v76
	ds_write_b32 v85, v77 offset:16
	ds_write_b32 v85, v78 offset:32
	ds_write_b32 v85, v79 offset:48
	ds_write_b32 v85, v72 offset:256
	ds_write_b32 v85, v73 offset:272
	ds_write_b32 v85, v74 offset:288
	ds_write_b32 v85, v75 offset:304
	ds_write_b32 v85, v68 offset:8192
	ds_write_b32 v85, v69 offset:8208
	ds_write_b32 v85, v70 offset:8224
	ds_write_b32 v85, v71 offset:8240
	ds_write_b32 v85, v64 offset:8448
	ds_write_b32 v85, v65 offset:8464
	ds_write_b32 v85, v66 offset:8480
	ds_write_b32 v85, v67 offset:8496
	s_mov_b64 exec, s[0:1]
	ds_read_b128 v[76:79], v86
	ds_read_b128 v[72:75], v86 offset:8192
	s_waitcnt lgkmcnt(0)
	global_store_dwordx4 v87, v[76:79], s[56:57]
	global_store_dwordx4 v87, v[72:75], s[56:57] offset:2048

; DI size_t vf_off(int h, int nblk, int krow, int d) { const int kk = krow & 31; return (((((size_t)h * nblk + (krow >> 5)) * 2 + (d >> 5)) * 2 + (kk >> 4)) * 64 + ((kk >> 2) & 1) * 32 + (d & 31)) * 8 + 4 * ((kk >> 3) & 1) + (kk & 3); }
;     DI void operator()(const AccT& acc, const Unit& u, int wr, int wc, int fr, int fq, LAS unsigned char*) const {
;     ...
;                     } else {
;                         bf16_t* vp = (bf16_t*)(ws + (isA ? WS_VTA : WS_VTB));
; #pragma unroll
;                         for (int bj = 0; bj < 2; ++bj)
; #pragma unroll
;                             for (int n = 0; n < 2; ++n)
; #pragma unroll
;                                 for (int j = 0; j < 4; ++j) {
;                                     const float mine = v[bj][n][j], oth = __shfl_xor(mine, 1);
;                                     if (!(fr & 1)) *(unsigned*)(vp + vf_off(h, krows >> 5, krow, 32 * bj + 16 * n + 4 * fq + j)) = pk2(mine, oth);
;                                 }
.LBB0_376:
	s_or_b64 exec, exec, s[0:1]
	v_lshrrev_b32_e32 v65, 6, v65
	v_or_b32_e32 v66, s90, v191
	v_mad_u64_u32 v[66:67], s[0:1], s31, v65, v[66:67]
	v_cmp_gt_i32_e32 vcc, s68, v64
	s_mov_b64 s[0:1], -1
	s_nop 0
	v_cndmask_b32_e32 v65, v66, v64, vcc
	v_ashrrev_i32_e32 v66, 5, v65
	s_andn2_b64 vcc, exec, s[50:51]
	v_ashrrev_i32_e32 v67, 31, v66
	s_cbranch_vccnz .LBB0_410
	v_readfirstlane_b32 s58, v65
	v_and_b32_e32 v68, 15, v198
	v_lshrrev_b32_e32 v69, 4, v198
	v_bfe_u32 v70, v68, 2, 1
	v_lshrrev_b32_e32 v71, 3, v68
	v_and_b32_e32 v68, 3, v68
	v_lshl_add_u32 v68, v71, 2, v68
	v_lshl_add_u32 v69, v70, 3, v69
	v_lshlrev_b32_e32 v69, 6, v69
	v_lshl_add_u32 v69, v68, 1, v69
	s_add_i32 s59, s64, 0xc000
	v_add_u32_e32 v69, s59, v69
	v_lshlrev_b32_e32 v71, 4, v198
	v_add_u32_e32 v70, s59, v71
	s_lshr_b32 s56, s58, 5
	s_add_u32 s56, s56, s46
	s_lshl_b32 s56, s56, 12
	s_and_b32 s57, s58, 16
	s_lshl_b32 s57, s57, 6
	s_add_u32 s56, s56, s57
	s_add_u32 s56, s56, s91
	s_add_u32 s56, s36, s56
	s_addc_u32 s57, s37, 0
	v_mov_b32_dpp v72, v44 quad_perm:[1,0,3,2] row_mask:0xf bank_mask:0xf
	v_mov_b32_dpp v73, v45 quad_perm:[1,0,3,2] row_mask:0xf bank_mask:0xf
	v_cvt_pk_bf16_f32 v44, v44, v72
	v_mov_b32_dpp v72, v46 quad_perm:[1,0,3,2] row_mask:0xf bank_mask:0xf
	v_cvt_pk_bf16_f32 v45, v45, v73
	v_mov_b32_dpp v73, v47 quad_perm:[1,0,3,2] row_mask:0xf bank_mask:0xf
	v_cvt_pk_bf16_f32 v46, v46, v72
	v_mov_b32_dpp v72, v40 quad_perm:[1,0,3,2] row_mask:0xf bank_mask:0xf
	v_cvt_pk_bf16_f32 v47, v47, v73
	v_mov_b32_dpp v73, v41 quad_perm:[1,0,3,2] row_mask:0xf bank_mask:0xf
	v_cvt_pk_bf16_f32 v40, v40, v72
	v_mov_b32_dpp v72, v42 quad_perm:[1,0,3,2] row_mask:0xf bank_mask:0xf
	v_cvt_pk_bf16_f32 v41, v41, v73
	v_mov_b32_dpp v73, v43 quad_perm:[1,0,3,2] row_mask:0xf bank_mask:0xf
	v_cvt_pk_bf16_f32 v42, v42, v72
	v_mov_b32_dpp v72, v36 quad_perm:[1,0,3,2] row_mask:0xf bank_mask:0xf
	v_cvt_pk_bf16_f32 v43, v43, v73
	v_mov_b32_dpp v73, v37 quad_perm:[1,0,3,2] row_mask:0xf bank_mask:0xf
	v_cvt_pk_bf16_f32 v36, v36, v72
	v_mov_b32_dpp v72, v38 quad_perm:[1,0,3,2] row_mask:0xf bank_mask:0xf
	v_cvt_pk_bf16_f32 v37, v37, v73
	v_mov_b32_dpp v73, v39 quad_perm:[1,0,3,2] row_mask:0xf bank_mask:0xf
	v_cvt_pk_bf16_f32 v38, v38, v72
	v_mov_b32_dpp v72, v32 quad_perm:[1,0,3,2] row_mask:0xf bank_mask:0xf
	v_cvt_pk_bf16_f32 v39, v39, v73
	v_mov_b32_dpp v73, v33 quad_perm:[1,0,3,2] row_mask:0xf bank_mask:0xf
	v_cvt_pk_bf16_f32 v32, v32, v72
	v_mov_b32_dpp v72, v34 quad_perm:[1,0,3,2] row_mask:0xf bank_mask:0xf
	v_cvt_pk_bf16_f32 v33, v33, v73
	v_mov_b32_dpp v73, v35 quad_perm:[1,0,3,2] row_mask:0xf bank_mask:0xf
	v_cvt_pk_bf16_f32 v34, v34, v72
	v_cvt_pk_bf16_f32 v35, v35, v73
	s_and_saveexec_b64 s[0:1], s[12:13]
	ds_write_b32 v69, v44
	ds_write_b32 v69, v45 offset:16
	ds_write_b32 v69, v46 offset:32
	ds_write_b32 v69, v47 offset:48
	ds_write_b32 v69, v40 offset:256
	ds_write_b32 v69, v41 offset:272
	ds_write_b32 v69, v42 offset:288
	ds_write_b32 v69, v43 offset:304
	ds_write_b32 v69, v36 offset:8192
	ds_write_b32 v69, v37 offset:8208
	ds_write_b32 v69, v38 offset:8224
	ds_write_b32 v69, v39 offset:8240
	ds_write_b32 v69, v32 offset:8448
	ds_write_b32 v69, v33 offset:8464
	ds_write_b32 v69, v34 offset:8480
	ds_write_b32 v69, v35 offset:8496
	s_mov_b64 exec, s[0:1]
	ds_read_b128 v[44:47], v70
	ds_read_b128 v[40:43], v70 offset:8192
	s_waitcnt lgkmcnt(0)
	global_store_dwordx4 v71, v[44:47], s[56:57]
	global_store_dwordx4 v71, v[40:43], s[56:57] offset:2048

; DI size_t vf_off(int h, int nblk, int krow, int d) { const int kk = krow & 31; return (((((size_t)h * nblk + (krow >> 5)) * 2 + (d >> 5)) * 2 + (kk >> 4)) * 64 + ((kk >> 2) & 1) * 32 + (d & 31)) * 8 + 4 * ((kk >> 3) & 1) + (kk & 3); }
;     DI void operator()(const AccT& acc, const Unit& u, int wr, int wc, int fr, int fq, LAS unsigned char*) const {
;     ...
;                     } else {
;                         bf16_t* vp = (bf16_t*)(ws + (isA ? WS_VTA : WS_VTB));
; #pragma unroll
;                         for (int bj = 0; bj < 2; ++bj)
; #pragma unroll
;                             for (int n = 0; n < 2; ++n)
; #pragma unroll
;                                 for (int j = 0; j < 4; ++j) {
;                                     const float mine = v[bj][n][j], oth = __shfl_xor(mine, 1);
;                                     if (!(fr & 1)) *(unsigned*)(vp + vf_off(h, krows >> 5, krow, 32 * bj + 16 * n + 4 * fq + j)) = pk2(mine, oth);
;                                 }
.LBB0_422:
	s_or_b64 exec, exec, s[0:1]
	v_lshrrev_b32_e32 v33, 6, v33
	v_or_b32_e32 v34, s90, v192
	v_mad_u64_u32 v[34:35], s[0:1], s31, v33, v[34:35]
	v_cmp_gt_i32_e32 vcc, s68, v32
	s_mov_b64 s[0:1], -1
	s_nop 0
	v_cndmask_b32_e32 v33, v34, v32, vcc
	v_ashrrev_i32_e32 v34, 5, v33
	s_andn2_b64 vcc, exec, s[50:51]
	v_ashrrev_i32_e32 v35, 31, v34
	s_cbranch_vccnz .LBB0_456
	v_readfirstlane_b32 s58, v33
	v_and_b32_e32 v36, 15, v198
	v_lshrrev_b32_e32 v37, 4, v198
	v_bfe_u32 v38, v36, 2, 1
	v_lshrrev_b32_e32 v39, 3, v36
	v_and_b32_e32 v36, 3, v36
	v_lshl_add_u32 v36, v39, 2, v36
	v_lshl_add_u32 v37, v38, 3, v37
	v_lshlrev_b32_e32 v37, 6, v37
	v_lshl_add_u32 v37, v36, 1, v37
	s_add_i32 s59, s64, 0xc000
	v_add_u32_e32 v37, s59, v37
	v_lshlrev_b32_e32 v39, 4, v198
	v_add_u32_e32 v38, s59, v39
	s_lshr_b32 s56, s58, 5
	s_add_u32 s56, s56, s46
	s_lshl_b32 s56, s56, 12
	s_and_b32 s57, s58, 16
	s_lshl_b32 s57, s57, 6
	s_add_u32 s56, s56, s57
	s_add_u32 s56, s56, s91
	s_add_u32 s56, s36, s56
	s_addc_u32 s57, s37, 0
	v_mov_b32_dpp v40, v28 quad_perm:[1,0,3,2] row_mask:0xf bank_mask:0xf
	v_mov_b32_dpp v41, v29 quad_perm:[1,0,3,2] row_mask:0xf bank_mask:0xf
	v_cvt_pk_bf16_f32 v28, v28, v40
	v_mov_b32_dpp v40, v30 quad_perm:[1,0,3,2] row_mask:0xf bank_mask:0xf
	v_cvt_pk_bf16_f32 v29, v29, v41
	v_mov_b32_dpp v41, v31 quad_perm:[1,0,3,2] row_mask:0xf bank_mask:0xf
	v_cvt_pk_bf16_f32 v30, v30, v40
	v_mov_b32_dpp v40, v24 quad_perm:[1,0,3,2] row_mask:0xf bank_mask:0xf
	v_cvt_pk_bf16_f32 v31, v31, v41
	v_mov_b32_dpp v41, v25 quad_perm:[1,0,3,2] row_mask:0xf bank_mask:0xf
	v_cvt_pk_bf16_f32 v24, v24, v40
	v_mov_b32_dpp v40, v26 quad_perm:[1,0,3,2] row_mask:0xf bank_mask:0xf
	v_cvt_pk_bf16_f32 v25, v25, v41
	v_mov_b32_dpp v41, v27 quad_perm:[1,0,3,2] row_mask:0xf bank_mask:0xf
	v_cvt_pk_bf16_f32 v26, v26, v40
	v_mov_b32_dpp v40, v20 quad_perm:[1,0,3,2] row_mask:0xf bank_mask:0xf
	v_cvt_pk_bf16_f32 v27, v27, v41
	v_mov_b32_dpp v41, v21 quad_perm:[1,0,3,2] row_mask:0xf bank_mask:0xf
	v_cvt_pk_bf16_f32 v20, v20, v40
	v_mov_b32_dpp v40, v22 quad_perm:[1,0,3,2] row_mask:0xf bank_mask:0xf
	v_cvt_pk_bf16_f32 v21, v21, v41
	v_mov_b32_dpp v41, v23 quad_perm:[1,0,3,2] row_mask:0xf bank_mask:0xf
	v_cvt_pk_bf16_f32 v22, v22, v40
	v_mov_b32_dpp v40, v16 quad_perm:[1,0,3,2] row_mask:0xf bank_mask:0xf
	v_cvt_pk_bf16_f32 v23, v23, v41
	v_mov_b32_dpp v41, v17 quad_perm:[1,0,3,2] row_mask:0xf bank_mask:0xf
	v_cvt_pk_bf16_f32 v16, v16, v40
	v_mov_b32_dpp v40, v18 quad_perm:[1,0,3,2] row_mask:0xf bank_mask:0xf
	v_cvt_pk_bf16_f32 v17, v17, v41
	v_mov_b32_dpp v41, v19 quad_perm:[1,0,3,2] row_mask:0xf bank_mask:0xf
	v_cvt_pk_bf16_f32 v18, v18, v40
	v_cvt_pk_bf16_f32 v19, v19, v41
	s_and_saveexec_b64 s[0:1], s[12:13]
	ds_write_b32 v37, v28
	ds_write_b32 v37, v29 offset:16
	ds_write_b32 v37, v30 offset:32
	ds_write_b32 v37, v31 offset:48
	ds_write_b32 v37, v24 offset:256
	ds_write_b32 v37, v25 offset:272
	ds_write_b32 v37, v26 offset:288
	ds_write_b32 v37, v27 offset:304
	ds_write_b32 v37, v20 offset:8192
	ds_write_b32 v37, v21 offset:8208
	ds_write_b32 v37, v22 offset:8224
	ds_write_b32 v37, v23 offset:8240
	ds_write_b32 v37, v16 offset:8448
	ds_write_b32 v37, v17 offset:8464
	ds_write_b32 v37, v18 offset:8480
	ds_write_b32 v37, v19 offset:8496
	s_mov_b64 exec, s[0:1]
	ds_read_b128 v[28:31], v38
	ds_read_b128 v[24:27], v38 offset:8192
	s_waitcnt lgkmcnt(0)
	global_store_dwordx4 v39, v[28:31], s[56:57]
	global_store_dwordx4 v39, v[24:27], s[56:57] offset:2048

; DI size_t vf_off(int h, int nblk, int krow, int d) { const int kk = krow & 31; return (((((size_t)h * nblk + (krow >> 5)) * 2 + (d >> 5)) * 2 + (kk >> 4)) * 64 + ((kk >> 2) & 1) * 32 + (d & 31)) * 8 + 4 * ((kk >> 3) & 1) + (kk & 3); }
;     DI void operator()(const AccT& acc, const Unit& u, int wr, int wc, int fr, int fq, LAS unsigned char*) const {
;     ...
;                     } else {
;                         bf16_t* vp = (bf16_t*)(ws + (isA ? WS_VTA : WS_VTB));
; #pragma unroll
;                         for (int bj = 0; bj < 2; ++bj)
; #pragma unroll
;                             for (int n = 0; n < 2; ++n)
; #pragma unroll
;                                 for (int j = 0; j < 4; ++j) {
;                                     const float mine = v[bj][n][j], oth = __shfl_xor(mine, 1);
;                                     if (!(fr & 1)) *(unsigned*)(vp + vf_off(h, krows >> 5, krow, 32 * bj + 16 * n + 4 * fq + j)) = pk2(mine, oth);
;                                 }
.LBB0_468:
	s_or_b64 exec, exec, s[0:1]
	v_lshrrev_b32_e32 v17, 6, v17
	v_or_b32_e32 v18, s90, v193
	v_mad_u64_u32 v[18:19], s[0:1], s31, v17, v[18:19]
	v_cmp_gt_i32_e32 vcc, s68, v16
	s_mov_b64 s[0:1], -1
	s_nop 0
	v_cndmask_b32_e32 v17, v18, v16, vcc
	v_ashrrev_i32_e32 v18, 5, v17
	s_andn2_b64 vcc, exec, s[50:51]
	v_ashrrev_i32_e32 v19, 31, v18
	s_cbranch_vccnz .LBB0_502
	v_readfirstlane_b32 s58, v17
	v_and_b32_e32 v20, 15, v198
	v_lshrrev_b32_e32 v21, 4, v198
	v_bfe_u32 v22, v20, 2, 1
	v_lshrrev_b32_e32 v23, 3, v20
	v_and_b32_e32 v20, 3, v20
	v_lshl_add_u32 v20, v23, 2, v20
	v_lshl_add_u32 v21, v22, 3, v21
	v_lshlrev_b32_e32 v21, 6, v21
	v_lshl_add_u32 v21, v20, 1, v21
	s_add_i32 s59, s64, 0xc000
	v_add_u32_e32 v21, s59, v21
	v_lshlrev_b32_e32 v23, 4, v198
	v_add_u32_e32 v22, s59, v23
	s_lshr_b32 s56, s58, 5
	s_add_u32 s56, s56, s46
	s_lshl_b32 s56, s56, 12
	s_and_b32 s57, s58, 16
	s_lshl_b32 s57, s57, 6
	s_add_u32 s56, s56, s57
	s_add_u32 s56, s56, s91
	s_add_u32 s56, s36, s56
	s_addc_u32 s57, s37, 0
	v_mov_b32_dpp v24, v12 quad_perm:[1,0,3,2] row_mask:0xf bank_mask:0xf
	v_mov_b32_dpp v25, v13 quad_perm:[1,0,3,2] row_mask:0xf bank_mask:0xf
	v_cvt_pk_bf16_f32 v12, v12, v24
	v_mov_b32_dpp v24, v14 quad_perm:[1,0,3,2] row_mask:0xf bank_mask:0xf
	v_cvt_pk_bf16_f32 v13, v13, v25
	v_mov_b32_dpp v25, v15 quad_perm:[1,0,3,2] row_mask:0xf bank_mask:0xf
	v_cvt_pk_bf16_f32 v14, v14, v24
	v_mov_b32_dpp v24, v8 quad_perm:[1,0,3,2] row_mask:0xf bank_mask:0xf
	v_cvt_pk_bf16_f32 v15, v15, v25
	v_mov_b32_dpp v25, v9 quad_perm:[1,0,3,2] row_mask:0xf bank_mask:0xf
	v_cvt_pk_bf16_f32 v8, v8, v24
	v_mov_b32_dpp v24, v10 quad_perm:[1,0,3,2] row_mask:0xf bank_mask:0xf
	v_cvt_pk_bf16_f32 v9, v9, v25
	v_mov_b32_dpp v25, v11 quad_perm:[1,0,3,2] row_mask:0xf bank_mask:0xf
	v_cvt_pk_bf16_f32 v10, v10, v24
	v_mov_b32_dpp v24, v4 quad_perm:[1,0,3,2] row_mask:0xf bank_mask:0xf
	v_cvt_pk_bf16_f32 v11, v11, v25
	v_mov_b32_dpp v25, v5 quad_perm:[1,0,3,2] row_mask:0xf bank_mask:0xf
	v_cvt_pk_bf16_f32 v4, v4, v24
	v_mov_b32_dpp v24, v6 quad_perm:[1,0,3,2] row_mask:0xf bank_mask:0xf
	v_cvt_pk_bf16_f32 v5, v5, v25
	v_mov_b32_dpp v25, v7 quad_perm:[1,0,3,2] row_mask:0xf bank_mask:0xf
	v_cvt_pk_bf16_f32 v6, v6, v24
	v_mov_b32_dpp v24, v0 quad_perm:[1,0,3,2] row_mask:0xf bank_mask:0xf
	v_cvt_pk_bf16_f32 v7, v7, v25
	v_mov_b32_dpp v25, v1 quad_perm:[1,0,3,2] row_mask:0xf bank_mask:0xf
	v_cvt_pk_bf16_f32 v0, v0, v24
	v_mov_b32_dpp v24, v2 quad_perm:[1,0,3,2] row_mask:0xf bank_mask:0xf
	v_cvt_pk_bf16_f32 v1, v1, v25
	v_mov_b32_dpp v25, v3 quad_perm:[1,0,3,2] row_mask:0xf bank_mask:0xf
	v_cvt_pk_bf16_f32 v2, v2, v24
	v_cvt_pk_bf16_f32 v3, v3, v25
	s_and_saveexec_b64 s[0:1], s[12:13]
	ds_write_b32 v21, v12
	ds_write_b32 v21, v13 offset:16
	ds_write_b32 v21, v14 offset:32
	ds_write_b32 v21, v15 offset:48
	ds_write_b32 v21, v8 offset:256
	ds_write_b32 v21, v9 offset:272
	ds_write_b32 v21, v10 offset:288
	ds_write_b32 v21, v11 offset:304
	ds_write_b32 v21, v4 offset:8192
	ds_write_b32 v21, v5 offset:8208
	ds_write_b32 v21, v6 offset:8224
	ds_write_b32 v21, v7 offset:8240
	ds_write_b32 v21, v0 offset:8448
	ds_write_b32 v21, v1 offset:8464
	ds_write_b32 v21, v2 offset:8480
	ds_write_b32 v21, v3 offset:8496
	s_mov_b64 exec, s[0:1]
	ds_read_b128 v[12:15], v22
	ds_read_b128 v[8:11], v22 offset:8192
	s_waitcnt lgkmcnt(0)
	global_store_dwordx4 v23, v[12:15], s[56:57]
	global_store_dwordx4 v23, v[8:11], s[56:57] offset:2048
